# v13 + grid barrier: non-leader workgroups poll the cross-XCD release generation directly instead of the per-XCD word bumped by their leader
# baseline (speedup 1.0000x reference)
; __device__ __forceinline__ unsigned xb_ld(unsigned* p)              { return __hip_atomic_load(p, __ATOMIC_RELAXED, __HIP_MEMORY_SCOPE_AGENT); }
; __device__ __forceinline__ unsigned xb_add(unsigned* p, unsigned v) { return __hip_atomic_fetch_add(p, v, __ATOMIC_RELAXED, __HIP_MEMORY_SCOPE_AGENT); }
; #define XB_SPIN(cond, bar) do { unsigned _sp = 0; while (cond) { __builtin_amdgcn_s_sleep(1); \
;     if ((++_sp & 255u) == 0u) { if (xb_ld(&(bar)[XB_TMO])) break; if (_sp > XB_SPIN_CAP) { atomicAdd(&(bar)[XB_TMO], 1u); break; } } } } while (0)
; __device__ __forceinline__ void xcd_barrier(const XcdBarrier& b) {
;     ...
;         const unsigned old = xb_add(&bar[XB_XSUB(b.x)], 1u);
;         const unsigned gen = old / nloc;
;         if (old + 1u == (gen + 1u) * nloc) {
;             __builtin_amdgcn_fence(__ATOMIC_RELEASE, "agent");
;             asm volatile("s_waitcnt vmcnt(0)" ::: "memory");
;             const unsigned og = xb_add(&bar[XB_TOP], 1u);
;             const unsigned tg = og / nx;
;             if (og + 1u == (tg + 1u) * nx) xb_add(&bar[XB_TOPGEN], 1u);
;             else XB_SPIN(xb_ld(&bar[XB_TOPGEN]) == tg, bar);
;             __builtin_amdgcn_fence(__ATOMIC_ACQUIRE, "agent");
;             xb_add(&bar[XB_XGEN(b.x)], 1u);
;             asm volatile("s_waitcnt vmcnt(0)" ::: "memory");
;         } else {
;             XB_SPIN(xb_ld(&bar[XB_XGEN(b.x)]) == gen, bar);
;             __builtin_amdgcn_fence(__ATOMIC_ACQUIRE, "agent");
;             asm volatile("s_waitcnt vmcnt(0)" ::: "memory");
;         }
.LBB0_95:
	s_or_b64 exec, exec, s[4:5]
	v_cvt_f32_u32_e32 v4, v2
	s_waitcnt vmcnt(0)
	v_readfirstlane_b32 s4, v3
	v_sub_u32_e32 v3, 0, v2
	v_rcp_iflag_f32_e32 v4, v4
	v_add_u32_e32 v5, s4, v1
	v_mul_f32_e32 v4, 0x4f7ffffe, v4
	v_cvt_u32_f32_e32 v4, v4
	v_mul_lo_u32 v1, v3, v4
	v_mul_hi_u32 v1, v4, v1
	v_add_u32_e32 v1, v4, v1
	v_mul_hi_u32 v1, v5, v1
	v_mul_lo_u32 v3, v1, v2
	v_sub_u32_e32 v3, v5, v3
	v_add_u32_e32 v4, 1, v1
	v_sub_u32_e32 v6, v3, v2
	v_cmp_ge_u32_e32 vcc, v3, v2
	s_nop 1
	v_cndmask_b32_e32 v1, v1, v4, vcc
	v_cndmask_b32_e32 v3, v3, v6, vcc
	v_add_u32_e32 v4, 1, v1
	v_cmp_ge_u32_e32 vcc, v3, v2
	v_add_u32_e32 v3, 1, v5
	s_nop 0
	v_cndmask_b32_e32 v1, v1, v4, vcc
	v_mul_lo_u32 v4, v2, v1
	v_add_u32_e32 v2, v4, v2
	v_cmp_ne_u32_e32 vcc, v3, v2
	s_and_saveexec_b64 s[4:5], vcc
	s_xor_b64 s[4:5], exec, s[4:5]
	s_cbranch_execz .LBB0_109
	s_waitcnt lgkmcnt(0)
	v_mov_b32_e32 v0, 0
	global_load_dword v2, v0, s[56:57] sc1
	s_waitcnt vmcnt(0)
	v_cmp_eq_u32_e32 vcc, v2, v1
	s_and_saveexec_b64 s[6:7], vcc
	s_cbranch_execz .LBB0_108
	s_mov_b32 s9, 1
	s_mov_b64 s[24:25], 0
	s_branch .LBB0_99

; __device__ __forceinline__ unsigned xb_ld(unsigned* p)              { return __hip_atomic_load(p, __ATOMIC_RELAXED, __HIP_MEMORY_SCOPE_AGENT); }
; __device__ __forceinline__ unsigned xb_add(unsigned* p, unsigned v) { return __hip_atomic_fetch_add(p, v, __ATOMIC_RELAXED, __HIP_MEMORY_SCOPE_AGENT); }
; #define XB_SPIN(cond, bar) do { unsigned _sp = 0; while (cond) { __builtin_amdgcn_s_sleep(1); \
;     if ((++_sp & 255u) == 0u) { if (xb_ld(&(bar)[XB_TMO])) break; if (_sp > XB_SPIN_CAP) { atomicAdd(&(bar)[XB_TMO], 1u); break; } } } } while (0)
; __device__ __forceinline__ void xcd_barrier(const XcdBarrier& b) {
;     ...
;             else XB_SPIN(xb_ld(&bar[XB_TOPGEN]) == tg, bar);
;             __builtin_amdgcn_fence(__ATOMIC_ACQUIRE, "agent");
;             xb_add(&bar[XB_XGEN(b.x)], 1u);
;             asm volatile("s_waitcnt vmcnt(0)" ::: "memory");
;         } else {
;             XB_SPIN(xb_ld(&bar[XB_XGEN(b.x)]) == gen, bar);
.LBB0_103:
	global_load_dword v2, v0, s[56:57] sc1
	s_add_i32 s9, s9, 1
	s_mov_b64 s[40:41], -1
	s_waitcnt vmcnt(0)
	v_cmp_ne_u32_e32 vcc, v2, v1
	s_orn2_b64 s[38:39], vcc, exec
	s_branch .LBB0_98

; __device__ __forceinline__ unsigned xb_ld(unsigned* p)              { return __hip_atomic_load(p, __ATOMIC_RELAXED, __HIP_MEMORY_SCOPE_AGENT); }
; __device__ __forceinline__ unsigned xb_add(unsigned* p, unsigned v) { return __hip_atomic_fetch_add(p, v, __ATOMIC_RELAXED, __HIP_MEMORY_SCOPE_AGENT); }
; #define XB_SPIN(cond, bar) do { unsigned _sp = 0; while (cond) { __builtin_amdgcn_s_sleep(1); \
;     if ((++_sp & 255u) == 0u) { if (xb_ld(&(bar)[XB_TMO])) break; if (_sp > XB_SPIN_CAP) { atomicAdd(&(bar)[XB_TMO], 1u); break; } } } } while (0)
; __device__ __forceinline__ void xcd_barrier(const XcdBarrier& b) {
;     ...
;         const unsigned old = xb_add(&bar[XB_XSUB(b.x)], 1u);
;         const unsigned gen = old / nloc;
;         if (old + 1u == (gen + 1u) * nloc) {
;             __builtin_amdgcn_fence(__ATOMIC_RELEASE, "agent");
;             asm volatile("s_waitcnt vmcnt(0)" ::: "memory");
;             const unsigned og = xb_add(&bar[XB_TOP], 1u);
;             const unsigned tg = og / nx;
;             if (og + 1u == (tg + 1u) * nx) xb_add(&bar[XB_TOPGEN], 1u);
;             else XB_SPIN(xb_ld(&bar[XB_TOPGEN]) == tg, bar);
;             __builtin_amdgcn_fence(__ATOMIC_ACQUIRE, "agent");
;             xb_add(&bar[XB_XGEN(b.x)], 1u);
;             asm volatile("s_waitcnt vmcnt(0)" ::: "memory");
;         } else {
;             XB_SPIN(xb_ld(&bar[XB_XGEN(b.x)]) == gen, bar);
.LBB0_168:
	s_or_b64 exec, exec, s[4:5]
	v_cvt_f32_u32_e32 v4, v2
	s_waitcnt vmcnt(0)
	v_readfirstlane_b32 s2, v3
	v_sub_u32_e32 v3, 0, v2
	v_rcp_iflag_f32_e32 v4, v4
	v_add_u32_e32 v5, s2, v1
	v_mul_f32_e32 v4, 0x4f7ffffe, v4
	v_cvt_u32_f32_e32 v4, v4
	v_mul_lo_u32 v1, v3, v4
	v_mul_hi_u32 v1, v4, v1
	v_add_u32_e32 v1, v4, v1
	v_mul_hi_u32 v1, v5, v1
	v_mul_lo_u32 v3, v1, v2
	v_sub_u32_e32 v3, v5, v3
	v_add_u32_e32 v4, 1, v1
	v_sub_u32_e32 v6, v3, v2
	v_cmp_ge_u32_e32 vcc, v3, v2
	s_nop 1
	v_cndmask_b32_e32 v1, v1, v4, vcc
	v_cndmask_b32_e32 v3, v3, v6, vcc
	v_add_u32_e32 v4, 1, v1
	v_cmp_ge_u32_e32 vcc, v3, v2
	v_add_u32_e32 v3, 1, v5
	s_nop 0
	v_cndmask_b32_e32 v1, v1, v4, vcc
	v_mul_lo_u32 v4, v2, v1
	v_add_u32_e32 v2, v4, v2
	v_cmp_ne_u32_e32 vcc, v3, v2
	s_and_saveexec_b64 s[2:3], vcc
	s_xor_b64 s[4:5], exec, s[2:3]
	s_cbranch_execz .LBB0_182
	s_waitcnt lgkmcnt(0)
	v_mov_b32_e32 v0, 0
	global_load_dword v2, v0, s[56:57] sc1
	s_waitcnt vmcnt(0)
	v_cmp_eq_u32_e32 vcc, v2, v1
	s_and_saveexec_b64 s[6:7], vcc
	s_cbranch_execz .LBB0_181
	s_mov_b32 s2, 1
	s_mov_b64 s[24:25], 0
	s_branch .LBB0_172

; __device__ __forceinline__ unsigned xb_ld(unsigned* p)              { return __hip_atomic_load(p, __ATOMIC_RELAXED, __HIP_MEMORY_SCOPE_AGENT); }
; __device__ __forceinline__ unsigned xb_add(unsigned* p, unsigned v) { return __hip_atomic_fetch_add(p, v, __ATOMIC_RELAXED, __HIP_MEMORY_SCOPE_AGENT); }
; #define XB_SPIN(cond, bar) do { unsigned _sp = 0; while (cond) { __builtin_amdgcn_s_sleep(1); \
;     if ((++_sp & 255u) == 0u) { if (xb_ld(&(bar)[XB_TMO])) break; if (_sp > XB_SPIN_CAP) { atomicAdd(&(bar)[XB_TMO], 1u); break; } } } } while (0)
; __device__ __forceinline__ void xcd_barrier(const XcdBarrier& b) {
;     ...
;             else XB_SPIN(xb_ld(&bar[XB_TOPGEN]) == tg, bar);
;             __builtin_amdgcn_fence(__ATOMIC_ACQUIRE, "agent");
;             xb_add(&bar[XB_XGEN(b.x)], 1u);
;             asm volatile("s_waitcnt vmcnt(0)" ::: "memory");
;         } else {
;             XB_SPIN(xb_ld(&bar[XB_XGEN(b.x)]) == gen, bar);
.LBB0_176:
	global_load_dword v2, v0, s[56:57] sc1
	s_add_i32 s2, s2, 1
	s_mov_b64 s[40:41], -1
	s_waitcnt vmcnt(0)
	v_cmp_ne_u32_e32 vcc, v2, v1
	s_orn2_b64 s[38:39], vcc, exec
	s_branch .LBB0_171

; __device__ __forceinline__ unsigned xb_ld(unsigned* p)              { return __hip_atomic_load(p, __ATOMIC_RELAXED, __HIP_MEMORY_SCOPE_AGENT); }
; __device__ __forceinline__ unsigned xb_add(unsigned* p, unsigned v) { return __hip_atomic_fetch_add(p, v, __ATOMIC_RELAXED, __HIP_MEMORY_SCOPE_AGENT); }
; #define XB_SPIN(cond, bar) do { unsigned _sp = 0; while (cond) { __builtin_amdgcn_s_sleep(1); \
;     if ((++_sp & 255u) == 0u) { if (xb_ld(&(bar)[XB_TMO])) break; if (_sp > XB_SPIN_CAP) { atomicAdd(&(bar)[XB_TMO], 1u); break; } } } } while (0)
; __device__ __forceinline__ void xcd_barrier(const XcdBarrier& b) {
;     ...
;         const unsigned old = xb_add(&bar[XB_XSUB(b.x)], 1u);
;         const unsigned gen = old / nloc;
;         if (old + 1u == (gen + 1u) * nloc) {
;             __builtin_amdgcn_fence(__ATOMIC_RELEASE, "agent");
;             asm volatile("s_waitcnt vmcnt(0)" ::: "memory");
;             const unsigned og = xb_add(&bar[XB_TOP], 1u);
;             const unsigned tg = og / nx;
;             if (og + 1u == (tg + 1u) * nx) xb_add(&bar[XB_TOPGEN], 1u);
;             else XB_SPIN(xb_ld(&bar[XB_TOPGEN]) == tg, bar);
;             __builtin_amdgcn_fence(__ATOMIC_ACQUIRE, "agent");
;             xb_add(&bar[XB_XGEN(b.x)], 1u);
;             asm volatile("s_waitcnt vmcnt(0)" ::: "memory");
;         } else {
;             XB_SPIN(xb_ld(&bar[XB_XGEN(b.x)]) == gen, bar);
.LBB0_274:
	s_or_b64 exec, exec, s[4:5]
	v_cvt_f32_u32_e32 v4, v2
	s_waitcnt vmcnt(0)
	v_readfirstlane_b32 s2, v3
	v_sub_u32_e32 v3, 0, v2
	v_rcp_iflag_f32_e32 v4, v4
	v_add_u32_e32 v5, s2, v1
	v_mul_f32_e32 v4, 0x4f7ffffe, v4
	v_cvt_u32_f32_e32 v4, v4
	v_mul_lo_u32 v1, v3, v4
	v_mul_hi_u32 v1, v4, v1
	v_add_u32_e32 v1, v4, v1
	v_mul_hi_u32 v1, v5, v1
	v_mul_lo_u32 v3, v1, v2
	v_sub_u32_e32 v3, v5, v3
	v_add_u32_e32 v4, 1, v1
	v_cmp_ge_u32_e32 vcc, v3, v2
	s_nop 1
	v_cndmask_b32_e32 v1, v1, v4, vcc
	v_sub_u32_e32 v4, v3, v2
	v_cndmask_b32_e32 v3, v3, v4, vcc
	v_add_u32_e32 v4, 1, v1
	v_cmp_ge_u32_e32 vcc, v3, v2
	v_add_u32_e32 v3, 1, v5
	s_nop 0
	v_cndmask_b32_e32 v1, v1, v4, vcc
	v_mul_lo_u32 v4, v2, v1
	v_add_u32_e32 v2, v4, v2
	v_cmp_ne_u32_e32 vcc, v3, v2
	s_and_saveexec_b64 s[2:3], vcc
	s_xor_b64 s[4:5], exec, s[2:3]
	s_cbranch_execz .LBB0_288
	s_waitcnt lgkmcnt(0)
	v_mov_b32_e32 v0, 0
	global_load_dword v2, v0, s[56:57] sc1
	s_waitcnt vmcnt(0)
	v_cmp_eq_u32_e32 vcc, v2, v1
	s_and_saveexec_b64 s[6:7], vcc
	s_cbranch_execz .LBB0_287
	s_mov_b32 s2, 1
	s_mov_b64 s[20:21], 0
	s_branch .LBB0_278

; __device__ __forceinline__ unsigned xb_ld(unsigned* p)              { return __hip_atomic_load(p, __ATOMIC_RELAXED, __HIP_MEMORY_SCOPE_AGENT); }
; __device__ __forceinline__ unsigned xb_add(unsigned* p, unsigned v) { return __hip_atomic_fetch_add(p, v, __ATOMIC_RELAXED, __HIP_MEMORY_SCOPE_AGENT); }
; #define XB_SPIN(cond, bar) do { unsigned _sp = 0; while (cond) { __builtin_amdgcn_s_sleep(1); \
;     if ((++_sp & 255u) == 0u) { if (xb_ld(&(bar)[XB_TMO])) break; if (_sp > XB_SPIN_CAP) { atomicAdd(&(bar)[XB_TMO], 1u); break; } } } } while (0)
; __device__ __forceinline__ void xcd_barrier(const XcdBarrier& b) {
;     ...
;         const unsigned old = xb_add(&bar[XB_XSUB(b.x)], 1u);
;         const unsigned gen = old / nloc;
;         if (old + 1u == (gen + 1u) * nloc) {
;             __builtin_amdgcn_fence(__ATOMIC_RELEASE, "agent");
;             asm volatile("s_waitcnt vmcnt(0)" ::: "memory");
;             const unsigned og = xb_add(&bar[XB_TOP], 1u);
;             const unsigned tg = og / nx;
;             if (og + 1u == (tg + 1u) * nx) xb_add(&bar[XB_TOPGEN], 1u);
;             else XB_SPIN(xb_ld(&bar[XB_TOPGEN]) == tg, bar);
;             __builtin_amdgcn_fence(__ATOMIC_ACQUIRE, "agent");
;             xb_add(&bar[XB_XGEN(b.x)], 1u);
;             asm volatile("s_waitcnt vmcnt(0)" ::: "memory");
;         } else {
;             XB_SPIN(xb_ld(&bar[XB_XGEN(b.x)]) == gen, bar);
.LBB0_392:
	s_or_b64 exec, exec, s[4:5]
	v_cvt_f32_u32_e32 v4, v2
	s_waitcnt vmcnt(0)
	v_readfirstlane_b32 s2, v3
	v_sub_u32_e32 v3, 0, v2
	v_rcp_iflag_f32_e32 v4, v4
	v_add_u32_e32 v5, s2, v1
	v_mul_f32_e32 v4, 0x4f7ffffe, v4
	v_cvt_u32_f32_e32 v4, v4
	v_mul_lo_u32 v1, v3, v4
	v_mul_hi_u32 v1, v4, v1
	v_add_u32_e32 v1, v4, v1
	v_mul_hi_u32 v1, v5, v1
	v_mul_lo_u32 v3, v1, v2
	v_sub_u32_e32 v3, v5, v3
	v_add_u32_e32 v4, 1, v1
	v_cmp_ge_u32_e32 vcc, v3, v2
	s_nop 1
	v_cndmask_b32_e32 v1, v1, v4, vcc
	v_sub_u32_e32 v4, v3, v2
	v_cndmask_b32_e32 v3, v3, v4, vcc
	v_add_u32_e32 v4, 1, v1
	v_cmp_ge_u32_e32 vcc, v3, v2
	v_add_u32_e32 v3, 1, v5
	s_nop 0
	v_cndmask_b32_e32 v1, v1, v4, vcc
	v_mul_lo_u32 v4, v2, v1
	v_add_u32_e32 v2, v4, v2
	v_cmp_ne_u32_e32 vcc, v3, v2
	s_and_saveexec_b64 s[2:3], vcc
	s_xor_b64 s[4:5], exec, s[2:3]
	s_cbranch_execz .LBB0_406
	s_waitcnt lgkmcnt(0)
	v_mov_b32_e32 v0, 0
	v_readlane_b32 s98, v241, 59
	v_readlane_b32 s99, v241, 60
	s_nop 4
	global_load_dword v2, v0, s[98:99] sc1
	s_waitcnt vmcnt(0)
	v_cmp_eq_u32_e32 vcc, v2, v1
	s_and_saveexec_b64 s[6:7], vcc
	s_cbranch_execz .LBB0_405
	s_mov_b32 s2, 1
	s_mov_b64 s[8:9], 0
	s_branch .LBB0_396

; __device__ __forceinline__ unsigned xb_ld(unsigned* p)              { return __hip_atomic_load(p, __ATOMIC_RELAXED, __HIP_MEMORY_SCOPE_AGENT); }
; __device__ __forceinline__ unsigned xb_add(unsigned* p, unsigned v) { return __hip_atomic_fetch_add(p, v, __ATOMIC_RELAXED, __HIP_MEMORY_SCOPE_AGENT); }
; #define XB_SPIN(cond, bar) do { unsigned _sp = 0; while (cond) { __builtin_amdgcn_s_sleep(1); \
;     if ((++_sp & 255u) == 0u) { if (xb_ld(&(bar)[XB_TMO])) break; if (_sp > XB_SPIN_CAP) { atomicAdd(&(bar)[XB_TMO], 1u); break; } } } } while (0)
; __device__ __forceinline__ void xcd_barrier(const XcdBarrier& b) {
;     ...
;             else XB_SPIN(xb_ld(&bar[XB_TOPGEN]) == tg, bar);
;             __builtin_amdgcn_fence(__ATOMIC_ACQUIRE, "agent");
;             xb_add(&bar[XB_XGEN(b.x)], 1u);
;             asm volatile("s_waitcnt vmcnt(0)" ::: "memory");
;         } else {
;             XB_SPIN(xb_ld(&bar[XB_XGEN(b.x)]) == gen, bar);
.LBB0_400:
	global_load_dword v2, v0, s[98:99] sc1
	s_add_i32 s2, s2, 1
	s_mov_b64 s[24:25], -1
	s_waitcnt vmcnt(0)
	v_cmp_ne_u32_e32 vcc, v2, v1
	s_orn2_b64 s[22:23], vcc, exec
	s_branch .LBB0_395

; __device__ __forceinline__ unsigned xb_ld(unsigned* p)              { return __hip_atomic_load(p, __ATOMIC_RELAXED, __HIP_MEMORY_SCOPE_AGENT); }
; __device__ __forceinline__ unsigned xb_add(unsigned* p, unsigned v) { return __hip_atomic_fetch_add(p, v, __ATOMIC_RELAXED, __HIP_MEMORY_SCOPE_AGENT); }
; #define XB_SPIN(cond, bar) do { unsigned _sp = 0; while (cond) { __builtin_amdgcn_s_sleep(1); \
;     if ((++_sp & 255u) == 0u) { if (xb_ld(&(bar)[XB_TMO])) break; if (_sp > XB_SPIN_CAP) { atomicAdd(&(bar)[XB_TMO], 1u); break; } } } } while (0)
; __device__ __forceinline__ void xcd_barrier(const XcdBarrier& b) {
;     ...
;             else XB_SPIN(xb_ld(&bar[XB_TOPGEN]) == tg, bar);
;             __builtin_amdgcn_fence(__ATOMIC_ACQUIRE, "agent");
;             xb_add(&bar[XB_XGEN(b.x)], 1u);
;             asm volatile("s_waitcnt vmcnt(0)" ::: "memory");
;         } else {
;             XB_SPIN(xb_ld(&bar[XB_XGEN(b.x)]) == gen, bar);
.LBB0_463:
	global_load_dword v2, v0, s[98:99] sc1
	s_add_i32 s2, s2, 1
	s_mov_b64 s[38:39], -1
	s_waitcnt vmcnt(0)
	v_cmp_ne_u32_e32 vcc, v2, v1
	s_orn2_b64 s[24:25], vcc, exec
	s_branch .LBB0_458

; __device__ __forceinline__ unsigned xb_ld(unsigned* p)              { return __hip_atomic_load(p, __ATOMIC_RELAXED, __HIP_MEMORY_SCOPE_AGENT); }
; __device__ __forceinline__ unsigned xb_add(unsigned* p, unsigned v) { return __hip_atomic_fetch_add(p, v, __ATOMIC_RELAXED, __HIP_MEMORY_SCOPE_AGENT); }
; #define XB_SPIN(cond, bar) do { unsigned _sp = 0; while (cond) { __builtin_amdgcn_s_sleep(1); \
;     if ((++_sp & 255u) == 0u) { if (xb_ld(&(bar)[XB_TMO])) break; if (_sp > XB_SPIN_CAP) { atomicAdd(&(bar)[XB_TMO], 1u); break; } } } } while (0)
; __device__ __forceinline__ void xcd_barrier(const XcdBarrier& b) {
;     ...
;             else XB_SPIN(xb_ld(&bar[XB_TOPGEN]) == tg, bar);
;             __builtin_amdgcn_fence(__ATOMIC_ACQUIRE, "agent");
;             xb_add(&bar[XB_XGEN(b.x)], 1u);
;             asm volatile("s_waitcnt vmcnt(0)" ::: "memory");
;         } else {
;             XB_SPIN(xb_ld(&bar[XB_XGEN(b.x)]) == gen, bar);
.LBB0_549:
	global_load_dword v2, v0, s[98:99] sc1
	s_add_i32 s2, s2, 1
	s_mov_b64 s[18:19], -1
	s_waitcnt vmcnt(0)
	v_cmp_ne_u32_e32 vcc, v2, v1
	s_orn2_b64 s[16:17], vcc, exec
	s_branch .LBB0_544

; __device__ __forceinline__ unsigned xb_ld(unsigned* p)              { return __hip_atomic_load(p, __ATOMIC_RELAXED, __HIP_MEMORY_SCOPE_AGENT); }
; __device__ __forceinline__ unsigned xb_add(unsigned* p, unsigned v) { return __hip_atomic_fetch_add(p, v, __ATOMIC_RELAXED, __HIP_MEMORY_SCOPE_AGENT); }
; #define XB_SPIN(cond, bar) do { unsigned _sp = 0; while (cond) { __builtin_amdgcn_s_sleep(1); \
;     if ((++_sp & 255u) == 0u) { if (xb_ld(&(bar)[XB_TMO])) break; if (_sp > XB_SPIN_CAP) { atomicAdd(&(bar)[XB_TMO], 1u); break; } } } } while (0)
; __device__ __forceinline__ void xcd_barrier(const XcdBarrier& b) {
;     ...
;             else XB_SPIN(xb_ld(&bar[XB_TOPGEN]) == tg, bar);
;             __builtin_amdgcn_fence(__ATOMIC_ACQUIRE, "agent");
;             xb_add(&bar[XB_XGEN(b.x)], 1u);
;             asm volatile("s_waitcnt vmcnt(0)" ::: "memory");
;         } else {
;             XB_SPIN(xb_ld(&bar[XB_XGEN(b.x)]) == gen, bar);
.LBB0_604:
	global_load_dword v2, v0, s[98:99] sc1
	s_add_i32 s2, s2, 1
	s_mov_b64 s[14:15], -1
	s_waitcnt vmcnt(0)
	v_cmp_ne_u32_e32 vcc, v2, v1
	s_orn2_b64 s[12:13], vcc, exec
	s_branch .LBB0_599

; __device__ __forceinline__ unsigned xb_ld(unsigned* p)              { return __hip_atomic_load(p, __ATOMIC_RELAXED, __HIP_MEMORY_SCOPE_AGENT); }
; __device__ __forceinline__ unsigned xb_add(unsigned* p, unsigned v) { return __hip_atomic_fetch_add(p, v, __ATOMIC_RELAXED, __HIP_MEMORY_SCOPE_AGENT); }
; #define XB_SPIN(cond, bar) do { unsigned _sp = 0; while (cond) { __builtin_amdgcn_s_sleep(1); \
;     if ((++_sp & 255u) == 0u) { if (xb_ld(&(bar)[XB_TMO])) break; if (_sp > XB_SPIN_CAP) { atomicAdd(&(bar)[XB_TMO], 1u); break; } } } } while (0)
; __device__ __forceinline__ void xcd_barrier(const XcdBarrier& b) {
;     ...
;         const unsigned old = xb_add(&bar[XB_XSUB(b.x)], 1u);
;         const unsigned gen = old / nloc;
;         if (old + 1u == (gen + 1u) * nloc) {
;             __builtin_amdgcn_fence(__ATOMIC_RELEASE, "agent");
;             asm volatile("s_waitcnt vmcnt(0)" ::: "memory");
;             const unsigned og = xb_add(&bar[XB_TOP], 1u);
;             const unsigned tg = og / nx;
;             if (og + 1u == (tg + 1u) * nx) xb_add(&bar[XB_TOPGEN], 1u);
;             else XB_SPIN(xb_ld(&bar[XB_TOPGEN]) == tg, bar);
;             __builtin_amdgcn_fence(__ATOMIC_ACQUIRE, "agent");
;             xb_add(&bar[XB_XGEN(b.x)], 1u);
;             asm volatile("s_waitcnt vmcnt(0)" ::: "memory");
;         } else {
;             XB_SPIN(xb_ld(&bar[XB_XGEN(b.x)]) == gen, bar);
.LBB0_688:
	s_or_b64 exec, exec, s[8:9]
	v_cvt_f32_u32_e32 v4, v2
	s_waitcnt vmcnt(0)
	v_readfirstlane_b32 s2, v3
	v_sub_u32_e32 v3, 0, v2
	v_rcp_iflag_f32_e32 v4, v4
	v_add_u32_e32 v5, s2, v1
	v_mul_f32_e32 v4, 0x4f7ffffe, v4
	v_cvt_u32_f32_e32 v4, v4
	v_mul_lo_u32 v1, v3, v4
	v_mul_hi_u32 v1, v4, v1
	v_add_u32_e32 v1, v4, v1
	v_mul_hi_u32 v1, v5, v1
	v_mul_lo_u32 v3, v1, v2
	v_sub_u32_e32 v3, v5, v3
	v_add_u32_e32 v4, 1, v1
	v_cmp_ge_u32_e32 vcc, v3, v2
	s_nop 1
	v_cndmask_b32_e32 v1, v1, v4, vcc
	v_sub_u32_e32 v4, v3, v2
	v_cndmask_b32_e32 v3, v3, v4, vcc
	v_add_u32_e32 v4, 1, v1
	v_cmp_ge_u32_e32 vcc, v3, v2
	v_add_u32_e32 v3, 1, v5
	s_nop 0
	v_cndmask_b32_e32 v1, v1, v4, vcc
	v_mul_lo_u32 v4, v2, v1
	v_add_u32_e32 v2, v4, v2
	v_cmp_ne_u32_e32 vcc, v3, v2
	s_and_saveexec_b64 s[2:3], vcc
	s_xor_b64 s[8:9], exec, s[2:3]
	s_cbranch_execz .LBB0_702
	s_waitcnt lgkmcnt(0)
	v_mov_b32_e32 v0, 0
	v_readlane_b32 s98, v241, 59
	v_readlane_b32 s99, v241, 60
	s_nop 4
	global_load_dword v2, v0, s[98:99] sc1
	s_waitcnt vmcnt(0)
	v_cmp_eq_u32_e32 vcc, v2, v1
	s_and_saveexec_b64 s[10:11], vcc
	s_cbranch_execz .LBB0_701
	s_mov_b32 s2, 1
	s_mov_b64 s[12:13], 0
	s_branch .LBB0_692
